# phase7 SWA: sink and q-fragment loads hoisted to item top ahead of K/V window loads
# speedup vs baseline: 1.0001x; 1.0001x over previous
.LBB0_1227:
	s_and_b32 s52, s64, 15
	s_ashr_i32 s8, s64, 5
	s_lshl_b32 s53, s52, 7
	s_bfe_u32 s54, s64, 0x10004
	v_readlane_b32 s74, v247, 6
	v_readlane_b32 s75, v247, 7
	v_readfirstlane_b32 s10, v208
	s_lshr_b32 s10, s10, 6
	s_lshl_b32 s11, s54, 3
	s_add_i32 s10, s10, s11
	s_lshl_b32 s11, s10, 2
	s_ashr_i32 s9, s8, 31
	s_lshl_b64 s[50:51], s[8:9], 11
	v_or_b32_e32 v4, s53, v211
	v_or_b32_e32 v3, s50, v4
	v_mov_b64_e32 v[4:5], s[24:25]
	v_mad_u64_u32 v[4:5], s[12:13], v3, s60, v[4:5]
	v_mad_i32_i24 v5, s51, v230, v5
	s_lshl_b32 s16, s10, 7
	v_lshl_add_u64 v[4:5], v[4:5], 0, s[16:17]
	v_mov_b32_e32 v185, v2
	v_mov_b32_e32 v3, s11
	v_lshl_add_u64 v[186:187], v[4:5], 0, v[184:185]
	global_load_dword v234, v3, s[74:75]
	global_load_dwordx4 v[146:149], v[186:187], off
	global_load_dwordx4 v[150:153], v[186:187], off offset:32
	global_load_dwordx4 v[154:157], v[186:187], off offset:64
	global_load_dwordx4 v[158:161], v[186:187], off offset:96
	s_add_i32 s12, s53, 0xffffff80
	s_mul_i32 s10, s8, 0x900000
	s_mul_hi_i32 s9, s8, 0x900000
	s_add_u32 s10, s20, s10
	s_addc_u32 s9, s21, s9
	s_lshl_b32 s11, s54, 7
	s_add_u32 s10, s10, s11
	s_addc_u32 s11, s9, 0
	v_lshl_add_u64 v[4:5], s[10:11], 0, v[178:179]
	s_cmp_eq_u32 s52, 0
	v_lshl_add_u64 v[10:11], v[4:5], 0, s[26:27]
	s_cbranch_scc1 .LBB0_1229
	v_or_b32_e32 v3, s12, v1
	v_mad_u64_u32 v[4:5], s[10:11], v3, s60, v[10:11]
	global_load_dwordx4 v[4:7], v[4:5], off
	s_branch .LBB0_1230

.LBB0_1252:
	s_or_saveexec_b64 s[10:11], s[10:11]
	s_ashr_i32 s9, s8, 31
	s_xor_b64 exec, exec, s[10:11]
	ds_write_b128 v224, v[36:39] offset:36864
	s_or_b64 exec, exec, s[10:11]
	v_readfirstlane_b32 s10, v208
	s_lshr_b32 s10, s10, 6
	s_lshl_b32 s11, s54, 3
	s_add_i32 s10, s10, s11
	s_lshl_b32 s11, s10, 2
	v_readlane_b32 s68, v247, 0
	v_mov_b32_e32 v3, s11
	v_readlane_b32 s74, v247, 6
	v_readlane_b32 s75, v247, 7
	s_lshl_b64 s[50:51], s[8:9], 11
	v_or_b32_e32 v181, s53, v211
	s_waitcnt lgkmcnt(0)
	s_barrier
	s_nop 0
	v_or_b32_e32 v3, s50, v181
	v_mov_b64_e32 v[4:5], s[24:25]
	v_mad_u64_u32 v[4:5], s[8:9], v3, s60, v[4:5]
	v_mad_i32_i24 v5, s51, v230, v5
	s_lshl_b32 s16, s10, 7
	v_lshl_add_u64 v[4:5], v[4:5], 0, s[16:17]
	v_mov_b32_e32 v185, v2
	v_lshl_add_u64 v[186:187], v[4:5], 0, v[184:185]
	s_add_i32 s10, s10, 1
	v_cvt_f32_u32_e32 v34, s10
	v_mov_b32_e32 v18, v2
	v_mov_b32_e32 v19, v2
	v_mov_b32_e32 v20, v2
	v_mul_f32_e32 v34, -0.5, v34
	v_exp_f32_e32 v34, v34
	v_mov_b32_e32 v21, v2
	v_mov_b32_e32 v22, v2
	v_mov_b32_e32 v23, v2
	v_mul_f32_e32 v191, 0x3fb8aa3b, v34
	v_mov_b32_e32 v24, v2
	v_mov_b32_e32 v25, v2
	v_mov_b32_e32 v26, v2
	v_mov_b32_e32 v27, v2
	v_mov_b32_e32 v28, v2
	v_mov_b32_e32 v29, v2
	v_mov_b32_e32 v30, v2
	v_mov_b32_e32 v31, v2
	v_mov_b32_e32 v32, v2
	v_mov_b32_e32 v33, v2
	v_mov_b32_e32 v34, v191
	v_mov_b32_e32 v3, v2
	v_mov_b32_e32 v4, v2
	v_mov_b32_e32 v5, v2
	v_mov_b32_e32 v6, v2
	v_mov_b32_e32 v7, v2
	v_mov_b32_e32 v8, v2
	v_mov_b32_e32 v9, v2
	v_mov_b32_e32 v10, v2
	v_mov_b32_e32 v11, v2
	v_mov_b32_e32 v12, v2
	v_mov_b32_e32 v13, v2
	v_mov_b32_e32 v14, v2
	v_mov_b32_e32 v15, v2
	v_mov_b32_e32 v16, v2
	v_mov_b32_e32 v17, v2
	s_cmp_lg_u32 s52, 0
	s_mov_b32 s65, 0
	v_mov_b32_e32 v183, v218
	v_mov_b32_e32 v185, v217
	v_lshl_add_u64 v[188:189], v[176:177], 0, s[16:17]
	s_cselect_b64 s[52:53], -1, 0
	v_mul_f32_e32 v190, 0, v191
	v_readlane_b32 s69, v247, 1
	v_readlane_b32 s70, v247, 2
	v_readlane_b32 s71, v247, 3
	v_readlane_b32 s72, v247, 4
	v_readlane_b32 s73, v247, 5
	s_waitcnt vmcnt(4)
	v_pk_mul_f32 v[192:193], v[34:35], s[30:31] op_sel_hi:[0,1]
	v_pk_mul_f32 v[194:195], v[34:35], s[34:35] op_sel_hi:[0,1]
	v_pk_mul_f32 v[196:197], v[34:35], s[38:39] op_sel_hi:[0,1]
	v_pk_mul_f32 v[198:199], v[34:35], s[40:41] op_sel_hi:[0,1]
	v_pk_mul_f32 v[200:201], v[34:35], s[44:45] op_sel_hi:[0,1]
	v_pk_mul_f32 v[202:203], v[34:35], s[46:47] op_sel_hi:[0,1]
	v_pk_mul_f32 v[204:205], v[34:35], s[48:49] op_sel_hi:[0,1]
	v_mul_f32_e32 v234, 0x3fb8aa3b, v234
	v_mov_b64_e32 v[48:49], v[32:33]
	v_mov_b64_e32 v[46:47], v[30:31]
	v_mov_b64_e32 v[44:45], v[28:29]
	v_mov_b64_e32 v[42:43], v[26:27]
	v_mov_b64_e32 v[40:41], v[24:25]
	v_mov_b64_e32 v[38:39], v[22:23]
	v_mov_b64_e32 v[36:37], v[20:21]
	v_mov_b64_e32 v[34:35], v[18:19]
	v_mov_b64_e32 v[32:33], v[16:17]
	v_mov_b64_e32 v[30:31], v[14:15]
	v_mov_b64_e32 v[28:29], v[12:13]
	v_mov_b64_e32 v[26:27], v[10:11]
	v_mov_b64_e32 v[24:25], v[8:9]
	v_mov_b64_e32 v[22:23], v[6:7]
	v_mov_b64_e32 v[20:21], v[4:5]
	v_mov_b64_e32 v[18:19], v[2:3]
	s_branch .LBB0_1256
